# v16: GLA S5 store/MFMA interleave + logits MFMA hoist; attention fast tile path (K/V LDS staging and speculative first-half exp under QK MFMAs, exact fallback when row max updates)
# speedup vs baseline: 1.0056x; 1.0037x over previous
; __device__ __forceinline__ void phase_attn(const Frame& F, int l, bool last, int ai, int na) {
;     ...
;         AT_LOAD(0);
;     ...
;         __syncthreads();
;         AT_STORE(0);
;         if (ntile > 1) AT_LOAD(1);
;         for (int t = 0; t < ntile; ++t) {
;             const int bo = (t & 1) * AT_BUF;
;             __syncthreads();
;             if (t + 1 < ntile) { AT_STORE(AT_BUF - bo); if (t + 2 < ntile) AT_LOAD(t + 2); }
;             const int kpos0 = wlo + t * 64, q0w = qb * 128 + (w & 3) * 32;
;             const bool win = (t < nwin) && !(kpos0 <= q0w + 65 && kpos0 >= q0w - 97);
;             if ((t < nwin) && (kpos0 > q0w + 159 || kpos0 < q0w - 191)) continue;
.LBB0_609:
	s_add_i32 s10, s39, 4
	s_bitcmp1_b32 s10, 0
	s_cselect_b32 s40, 0x8c00, 0
	s_add_i32 s2, s39, 5
	s_cmp_ge_i32 s2, s31
	s_waitcnt lgkmcnt(0)
	s_barrier
	s_add_i32 s41, s27, s38
	s_cmp_ge_i32 s10, s28
	s_cbranch_scc1 .Lattn_fast
	s_cmp_lt_i32 s41, s35
	s_cbranch_scc1 .Lattn_slowtop
	s_cmp_le_i32 s41, s34
	s_cbranch_scc1 .Lattn_fast
.Lattn_slowtop:
	s_cmp_ge_i32 s2, s31
	s_cbranch_scc1 .LBB0_612
	s_sub_i32 s2, 0, s40
	v_add_u32_e32 v0, s2, v180
	s_mov_b32 s3, 0x5040100
	s_mov_b32 s11, 0x7060302
	v_add_u32_e32 v3, s2, v181
	s_waitcnt vmcnt(2)
	ds_write_b128 v0, v[148:151] offset:35840
	ds_write_b128 v0, v[144:147] offset:35856
	s_waitcnt vmcnt(0)
	v_perm_b32 v2, v156, v152, s3
	v_perm_b32 v4, v156, v152, s11
	ds_write_b32 v3, v2 offset:53248
	ds_write_b32 v3, v4 offset:53392
	v_perm_b32 v5, v157, v153, s3
	v_perm_b32 v6, v157, v153, s11
	ds_write_b32 v3, v5 offset:53536
	ds_write_b32 v3, v6 offset:53680
	v_perm_b32 v7, v158, v154, s3
	v_perm_b32 v8, v158, v154, s11
	ds_write_b32 v3, v7 offset:53824
	ds_write_b32 v3, v8 offset:53968
	v_perm_b32 v9, v159, v155, s3
	v_perm_b32 v10, v159, v155, s11
	ds_write_b32 v3, v9 offset:54112
	ds_write_b32 v3, v10 offset:54256
	s_add_i32 s2, s39, 6
	s_cmp_ge_i32 s2, s31
	s_cbranch_scc1 .LBB0_612
	s_cmp_lt_i32 s2, s28
	s_cselect_b32 s2, 0, s28
	s_cselect_b32 s3, s29, s26
	s_lshl_b32 s2, s2, 6
	s_sub_i32 s2, s3, s2
	s_add_i32 s11, s2, s38
	v_add_u32_e32 v0, s11, v226
	s_movk_i32 s41, 0x3400
	v_mad_i64_i32 v[2:3], s[2:3], v0, s41, v[174:175]
	v_add_u32_e32 v0, s11, v227
	global_load_dwordx4 v[144:147], v[2:3], off offset:16
	global_load_dwordx4 v[148:151], v[2:3], off
	v_mad_i64_i32 v[2:3], s[2:3], v0, s41, v[176:177]
	v_add_co_u32_e32 v4, vcc, 0x3000, v2
	s_movk_i32 s44, 0x3400
	s_nop 0
	v_addc_co_u32_e32 v5, vcc, 0, v3, vcc
	global_load_dwordx4 v[152:155], v[2:3], off offset:512
	global_load_dwordx4 v[156:159], v[4:5], off offset:1536

; #define LAS __attribute__((address_space(3)))
; __device__ __forceinline__ void phase_attn(const Frame& F, int l, bool last, int ai, int na) {
;     ...
;         AT_LOAD(0);
;     ...
;         __syncthreads();
;         AT_STORE(0);
;         if (ntile > 1) AT_LOAD(1);
;         for (int t = 0; t < ntile; ++t) {
;             const int bo = (t & 1) * AT_BUF;
;             __syncthreads();
;             if (t + 1 < ntile) { AT_STORE(AT_BUF - bo); if (t + 2 < ntile) AT_LOAD(t + 2); }
;             const int kpos0 = wlo + t * 64, q0w = qb * 128 + (w & 3) * 32;
;             const bool win = (t < nwin) && !(kpos0 <= q0w + 65 && kpos0 >= q0w - 97);
;             if ((t < nwin) && (kpos0 > q0w + 159 || kpos0 < q0w - 191)) continue;
;             f32x16 sacc[2];
; #pragma unroll
;             for (int kt = 0; kt < 2; ++kt) {
; #pragma unroll
;                 for (int e = 0; e < 16; ++e) sacc[kt][e] = 0.f;
; #pragma unroll
;                 for (int s = 0; s < 8; ++s) { const f16x8 a = *(const LAS f16x8*)(lds + bo + AT_K + ((kt * 32 + r32) * 136 + s * 16 + hh * 8) * 2);
;                     sacc[kt] = __builtin_amdgcn_mfma_f32_32x32x16_f16(a, qf[s], sacc[kt], 0, 0, 0); } }
.Lattn_fast:
	s_add_i32 s42, s39, 5
	s_cmp_ge_i32 s42, s31
	s_cselect_b32 s42, 1, 0
	s_add_i32 s43, s39, 6
	s_cmp_ge_i32 s43, s31
	s_cselect_b32 s43, 1, 0
	s_add_i32 s2, s40, 0
	s_sub_i32 s41, 0, s40
	s_mov_b32 s3, 0xf149f2ca
	v_add_u32_e32 v14, s2, v189
	ds_read_b128 v[2:5], v14
	ds_read_b128 v[6:9], v14 offset:32
	ds_read_b128 v[10:13], v14 offset:64
	ds_read_b128 v[200:203], v14 offset:96
	ds_read_b128 v[242:245], v14 offset:128
	ds_read_b128 v[246:249], v14 offset:160
	s_waitcnt lgkmcnt(5)
	v_mfma_f32_32x32x16_f16 v[96:111], v[2:5], v[112:115], 0
	ds_read_b128 v[2:5], v14 offset:192
	s_waitcnt lgkmcnt(5)
	v_mfma_f32_32x32x16_f16 v[96:111], v[6:9], v[116:119], v[96:111]
	ds_read_b128 v[6:9], v14 offset:224
	s_cmp_eq_u32 s42, 1
	s_cbranch_scc1 .Lf_noS
	s_waitcnt vmcnt(0)
	v_add_u32_e32 v80, s41, v180
	v_add_u32_e32 v81, s41, v181
	s_mov_b32 s10, 0x5040100
	s_mov_b32 s11, 0x7060302
	v_perm_b32 v82, v156, v152, s10
	v_perm_b32 v83, v156, v152, s11
	v_perm_b32 v84, v157, v153, s10
	v_perm_b32 v85, v157, v153, s11
	v_perm_b32 v86, v158, v154, s10
	v_perm_b32 v87, v158, v154, s11
	v_perm_b32 v88, v159, v155, s10
	v_perm_b32 v89, v159, v155, s11
.Lf_noS:
	s_waitcnt lgkmcnt(5)
	v_mfma_f32_32x32x16_f16 v[96:111], v[10:13], v[120:123], v[96:111]
	ds_read_b128 v[10:13], v14 offset:8704
	s_cmp_eq_u32 s42, 1
	s_cbranch_scc1 .Lf_noW1
	ds_write_b128 v80, v[148:151] offset:35840
	ds_write_b128 v80, v[144:147] offset:35856
	ds_write_b32 v81, v82 offset:53248
	ds_write_b32 v81, v83 offset:53392
	ds_write_b32 v81, v84 offset:53536
.Lf_noW1:
	s_waitcnt lgkmcnt(5)
	v_mfma_f32_32x32x16_f16 v[96:111], v[200:203], v[124:127], v[96:111]
	ds_read_b128 v[200:203], v14 offset:8736
	s_cmp_eq_u32 s42, 1
	s_cbranch_scc1 .Lf_noW2
	ds_write_b32 v81, v85 offset:53680
	ds_write_b32 v81, v86 offset:53824
	ds_write_b32 v81, v87 offset:53968
	ds_write_b32 v81, v88 offset:54112
	ds_write_b32 v81, v89 offset:54256
.Lf_noW2:
	s_waitcnt lgkmcnt(5)
	v_mfma_f32_32x32x16_f16 v[96:111], v[242:245], v[128:131], v[96:111]
	ds_read_b128 v[242:245], v14 offset:8768
	s_waitcnt lgkmcnt(5)
	v_mfma_f32_32x32x16_f16 v[96:111], v[246:249], v[132:135], v[96:111]
	ds_read_b128 v[246:249], v14 offset:8800
	s_waitcnt lgkmcnt(5)
	v_mfma_f32_32x32x16_f16 v[96:111], v[2:5], v[136:139], v[96:111]
	ds_read_b128 v[2:5], v14 offset:8832
	s_waitcnt lgkmcnt(5)
	v_mfma_f32_32x32x16_f16 v[96:111], v[6:9], v[140:143], v[96:111]
	ds_read_b128 v[6:9], v14 offset:8864
	s_waitcnt lgkmcnt(5)
	v_mfma_f32_32x32x16_f16 v[80:95], v[10:13], v[112:115], 0
	ds_read_b128 v[10:13], v14 offset:8896
	s_waitcnt lgkmcnt(5)
	v_mfma_f32_32x32x16_f16 v[80:95], v[200:203], v[116:119], v[80:95]
	ds_read_b128 v[200:203], v14 offset:8928
	s_cmp_eq_u32 s43, 1
	s_cbranch_scc1 .Lf_noL
	s_add_i32 s10, s39, 6
	s_cmp_lt_i32 s10, s28
	s_cselect_b32 s10, 0, s28
	s_cselect_b32 s11, s29, s26
	s_lshl_b32 s10, s10, 6
	s_sub_i32 s10, s11, s10
	s_add_i32 s11, s10, s38
	v_add_u32_e32 v231, s11, v226
	s_movk_i32 s44, 0x3400
	v_mad_i64_i32 v[14:15], s[42:43], v231, s44, v[174:175]
	v_add_u32_e32 v231, s11, v227
	global_load_dwordx4 v[144:147], v[14:15], off offset:16
	global_load_dwordx4 v[148:151], v[14:15], off
	v_mad_i64_i32 v[14:15], s[42:43], v231, s44, v[176:177]
	s_nop 0
	global_load_dwordx4 v[152:155], v[14:15], off offset:512
	v_add_co_u32_e32 v14, vcc, 0x3000, v14
	s_nop 1
	v_addc_co_u32_e32 v15, vcc, 0, v15, vcc
	global_load_dwordx4 v[156:159], v[14:15], off offset:1536
; #define LAS __attribute__((address_space(3)))
; __device__ __forceinline__ void phase_attn(const Frame& F, int l, bool last, int ai, int na) {
;     ...
;             float mx = -1e30f;
; #pragma unroll
;             for (int kt = 0; kt < 2; ++kt)
; #pragma unroll
;                 for (int e = 0; e < 16; ++e) {
;                     if (win) { const int kp = kpos0 + kt * 32 + (e & 3) + 8 * (e >> 2) + 4 * hh; const int dd = kp - qpos; if (dd > 128 || dd < -128) sacc[kt][e] = -1e30f; }
;                     mx = fmaxf(mx, sacc[kt][e]); }
;             mx = fmaxf(mx, __shfl_xor(mx, 32));
;             const bool upd = mx > mrun + 8.0f;
;             const bool anyupd = __builtin_amdgcn_ballot_w64(upd) != 0ull;
;             const float mnew = upd ? mx : mrun;
;             float rs = 0.f;
; #pragma unroll
;             for (int kt = 0; kt < 2; ++kt)
; #pragma unroll
;                 for (int g4 = 0; g4 < 4; ++g4) { float pv4[4];
; #pragma unroll
;                     for (int e = 0; e < 4; ++e) { pv4[e] = __builtin_amdgcn_exp2f(sacc[kt][g4 * 4 + e] - mnew); rs += pv4[e]; }
;                     *(LAS u32x2*)(Pw + (r32 * 72 + kt * 32 + g4 * 8 + hh * 4) * 2) = (u32x2){pk_f16(pv4[0], pv4[1]), pk_f16(pv4[2], pv4[3])}; }
;             rs += __shfl_xor(rs, 32);
;             if (anyupd) { const float alpha = __builtin_amdgcn_exp2f(mrun - mnew); lrun *= alpha;
; #pragma unroll
;                 for (int dt = 0; dt < 4; ++dt)
; #pragma unroll
;                     for (int e = 0; e < 16; ++e) oacc[dt][e] *= alpha; }
;             lrun += rs; mrun = mnew;
;             asm volatile("s_waitcnt lgkmcnt(0)" ::: "memory");
; #pragma unroll
;             for (int s = 0; s < 4; ++s) { const f16x8 pb = *(const LAS f16x8*)(Pw + (r32 * 72 + s * 16 + hh * 8) * 2);
; #pragma unroll
;                 for (int dt = 0; dt < 4; ++dt) { const f16x8 a = *(const LAS f16x8*)(lds + bo + AT_V + ((dt * 32 + r32) * 72 + s * 16 + hh * 8) * 2);
;                     oacc[dt] = __builtin_amdgcn_mfma_f32_32x32x16_f16(a, pb, oacc[dt], 0, 0, 0); } }
.Lf_noL:
	v_mov_b32_e32 v0, v230
	v_mov_b32_e32 v15, 0
	s_waitcnt lgkmcnt(5)
	v_mfma_f32_32x32x16_f16 v[80:95], v[242:245], v[120:123], v[80:95]
	s_waitcnt lgkmcnt(4)
	v_mfma_f32_32x32x16_f16 v[80:95], v[246:249], v[124:127], v[80:95]
	v_sub_f32_e32 v242, v96, v0
	v_exp_f32_e32 v242, v242
	v_sub_f32_e32 v243, v97, v0
	v_exp_f32_e32 v243, v243
	v_sub_f32_e32 v244, v98, v0
	v_exp_f32_e32 v244, v244
	v_sub_f32_e32 v245, v99, v0
	v_exp_f32_e32 v245, v245
	v_add_f32_e32 v15, v15, v242
	v_add_f32_e32 v15, v15, v243
	v_add_f32_e32 v15, v15, v244
	v_add_f32_e32 v15, v15, v245
	v_cvt_pk_f16_f32 v246, v242, v243
	v_cvt_pk_f16_f32 v247, v244, v245
	s_waitcnt lgkmcnt(3)
	v_mfma_f32_32x32x16_f16 v[80:95], v[2:5], v[128:131], v[80:95]
	v_sub_f32_e32 v242, v100, v0
	v_exp_f32_e32 v242, v242
	v_sub_f32_e32 v243, v101, v0
	v_exp_f32_e32 v243, v243
	v_sub_f32_e32 v244, v102, v0
	v_exp_f32_e32 v244, v244
	v_sub_f32_e32 v245, v103, v0
	v_exp_f32_e32 v245, v245
	v_add_f32_e32 v15, v15, v242
	v_add_f32_e32 v15, v15, v243
	v_add_f32_e32 v15, v15, v244
	v_add_f32_e32 v15, v15, v245
	v_cvt_pk_f16_f32 v248, v242, v243
	v_cvt_pk_f16_f32 v249, v244, v245
	ds_write2_b64 v228, v[246:247], v[248:249] offset1:2
	s_waitcnt lgkmcnt(2)
	v_mfma_f32_32x32x16_f16 v[80:95], v[6:9], v[132:135], v[80:95]
	v_sub_f32_e32 v242, v104, v0
	v_exp_f32_e32 v242, v242
	v_sub_f32_e32 v243, v105, v0
	v_exp_f32_e32 v243, v243
	v_sub_f32_e32 v244, v106, v0
	v_exp_f32_e32 v244, v244
	v_sub_f32_e32 v245, v107, v0
	v_exp_f32_e32 v245, v245
	v_add_f32_e32 v15, v15, v242
	v_add_f32_e32 v15, v15, v243
	v_add_f32_e32 v15, v15, v244
	v_add_f32_e32 v15, v15, v245
	v_cvt_pk_f16_f32 v246, v242, v243
	v_cvt_pk_f16_f32 v247, v244, v245
	s_waitcnt lgkmcnt(1)
	v_mfma_f32_32x32x16_f16 v[80:95], v[10:13], v[136:139], v[80:95]
	v_sub_f32_e32 v242, v108, v0
	v_exp_f32_e32 v242, v242
	v_sub_f32_e32 v243, v109, v0
	v_exp_f32_e32 v243, v243
	v_sub_f32_e32 v244, v110, v0
	v_exp_f32_e32 v244, v244
	v_sub_f32_e32 v245, v111, v0
	v_exp_f32_e32 v245, v245
	v_add_f32_e32 v15, v15, v242
	v_add_f32_e32 v15, v15, v243
	v_add_f32_e32 v15, v15, v244
	v_add_f32_e32 v15, v15, v245
	v_cvt_pk_f16_f32 v248, v242, v243
	v_cvt_pk_f16_f32 v249, v244, v245
	ds_write2_b64 v228, v[246:247], v[248:249] offset0:4 offset1:6
	s_waitcnt lgkmcnt(0)
	v_mfma_f32_32x32x16_f16 v[80:95], v[200:203], v[140:143], v[80:95]
	v_max3_f32 v4, v96, s3, v97
	v_max3_f32 v4, v4, v98, v99
	v_max3_f32 v4, v4, v100, v101
	v_max3_f32 v4, v4, v102, v103
	v_max3_f32 v4, v4, v104, v105
	v_max3_f32 v4, v4, v106, v107
	v_max3_f32 v4, v4, v108, v109
	v_max3_f32 v4, v4, v110, v111
	s_nop 3
	v_max3_f32 v4, v4, v80, v81
	v_max3_f32 v4, v4, v82, v83
	v_max3_f32 v4, v4, v84, v85
	v_max3_f32 v4, v4, v86, v87
	v_max3_f32 v4, v4, v88, v89
	v_max3_f32 v4, v4, v90, v91
	v_max3_f32 v4, v4, v92, v93
	v_max3_f32 v4, v4, v94, v95
	v_mov_b32_e32 v5, v4
	s_nop 1
	v_permlane32_swap_b32_e32 v4, v5
	v_max_f32_e32 v4, v4, v5
	v_add_f32_e32 v5, 0x41000000, v230
	v_cmp_gt_f32_e32 vcc, v4, v5
	s_cbranch_vccnz .Lattn_nomask
	v_add_u32_e32 v12, s12, v191
	v_add_u32_e32 v13, s2, v191
	ds_read_b128 v[200:203], v12
	ds_read_b128 v[242:245], v12 offset:32
	ds_read_b128 v[96:99], v13 offset:17408
	ds_read_b128 v[100:103], v13 offset:22016
	ds_read_b128 v[104:107], v13 offset:26624
	ds_read_b128 v[108:111], v13 offset:31232
	v_sub_f32_e32 v6, v80, v0
	v_exp_f32_e32 v6, v6
	v_sub_f32_e32 v7, v81, v0
	v_exp_f32_e32 v7, v7
	v_sub_f32_e32 v8, v82, v0
	v_exp_f32_e32 v8, v8
	v_sub_f32_e32 v9, v83, v0
	s_waitcnt lgkmcnt(3)
	v_mfma_f32_32x32x16_f16 v[64:79], v[96:99], v[200:203], v[64:79]
	ds_read_b128 v[96:99], v13 offset:17440
	v_exp_f32_e32 v9, v9
	v_add_f32_e32 v15, v15, v6
	v_add_f32_e32 v15, v15, v7
	v_add_f32_e32 v15, v15, v8
	v_add_f32_e32 v15, v15, v9
	v_cvt_pk_f16_f32 v2, v6, v7
	v_cvt_pk_f16_f32 v3, v8, v9
	s_waitcnt lgkmcnt(3)
	v_mfma_f32_32x32x16_f16 v[48:63], v[100:103], v[200:203], v[48:63]
	ds_read_b128 v[100:103], v13 offset:22048
	v_sub_f32_e32 v6, v84, v0
	v_exp_f32_e32 v6, v6
	v_sub_f32_e32 v7, v85, v0
	v_exp_f32_e32 v7, v7
	v_sub_f32_e32 v8, v86, v0
	v_exp_f32_e32 v8, v8
	v_sub_f32_e32 v9, v87, v0
	s_waitcnt lgkmcnt(3)
	v_mfma_f32_32x32x16_f16 v[32:47], v[104:107], v[200:203], v[32:47]
	ds_read_b128 v[104:107], v13 offset:26656
	v_exp_f32_e32 v9, v9
	v_add_f32_e32 v15, v15, v6
	v_add_f32_e32 v15, v15, v7
	v_add_f32_e32 v15, v15, v8
	v_add_f32_e32 v15, v15, v9
	v_cvt_pk_f16_f32 v4, v6, v7
	v_cvt_pk_f16_f32 v5, v8, v9
	ds_write2_b64 v228, v[2:3], v[4:5] offset0:8 offset1:10
	s_waitcnt lgkmcnt(4)
	v_mfma_f32_32x32x16_f16 v[16:31], v[108:111], v[200:203], v[16:31]
	ds_read_b128 v[108:111], v13 offset:31264
	v_sub_f32_e32 v6, v88, v0
	v_exp_f32_e32 v6, v6
	v_sub_f32_e32 v7, v89, v0
	v_exp_f32_e32 v7, v7
	v_sub_f32_e32 v8, v90, v0
	v_exp_f32_e32 v8, v8
	v_sub_f32_e32 v9, v91, v0
	s_waitcnt lgkmcnt(4)
	v_mfma_f32_32x32x16_f16 v[64:79], v[96:99], v[242:245], v[64:79]
	v_exp_f32_e32 v9, v9
	v_add_f32_e32 v15, v15, v6
	v_add_f32_e32 v15, v15, v7
	v_add_f32_e32 v15, v15, v8
	v_add_f32_e32 v15, v15, v9
	v_cvt_pk_f16_f32 v2, v6, v7
	v_cvt_pk_f16_f32 v3, v8, v9
	s_waitcnt lgkmcnt(3)
	v_mfma_f32_32x32x16_f16 v[48:63], v[100:103], v[242:245], v[48:63]
	v_sub_f32_e32 v6, v92, v0
	v_exp_f32_e32 v6, v6
	v_sub_f32_e32 v7, v93, v0
	v_exp_f32_e32 v7, v7
	v_sub_f32_e32 v8, v94, v0
	v_exp_f32_e32 v8, v8
	v_sub_f32_e32 v9, v95, v0
	s_waitcnt lgkmcnt(2)
	v_mfma_f32_32x32x16_f16 v[32:47], v[104:107], v[242:245], v[32:47]
	v_exp_f32_e32 v9, v9
	v_add_f32_e32 v15, v15, v6
	v_add_f32_e32 v15, v15, v7
	v_add_f32_e32 v15, v15, v8
	v_add_f32_e32 v15, v15, v9
	v_cvt_pk_f16_f32 v4, v6, v7
	v_cvt_pk_f16_f32 v5, v8, v9
	ds_write2_b64 v228, v[2:3], v[4:5] offset0:12 offset1:14
	ds_bpermute_b32 v14, v232, v15
	s_waitcnt lgkmcnt(2)
	v_mfma_f32_32x32x16_f16 v[16:31], v[108:111], v[242:245], v[16:31]
	ds_read_b128 v[246:249], v12 offset:64
	ds_read_b128 v[8:11], v12 offset:96
	ds_read_b128 v[80:83], v13 offset:17472
	ds_read_b128 v[84:87], v13 offset:22080
	ds_read_b128 v[88:91], v13 offset:26688
	ds_read_b128 v[92:95], v13 offset:31296
	ds_read_b128 v[96:99], v13 offset:17504
	ds_read_b128 v[100:103], v13 offset:22112
	ds_read_b128 v[104:107], v13 offset:26720
	ds_read_b128 v[108:111], v13 offset:31328
	s_waitcnt lgkmcnt(10)
	v_add_f32_e32 v15, v15, v14
	v_add_f32_e32 v171, v15, v171
	s_waitcnt lgkmcnt(7)
	v_mfma_f32_32x32x16_f16 v[64:79], v[80:83], v[246:249], v[64:79]
	s_waitcnt lgkmcnt(6)
	v_mfma_f32_32x32x16_f16 v[48:63], v[84:87], v[246:249], v[48:63]
	s_waitcnt lgkmcnt(5)
	v_mfma_f32_32x32x16_f16 v[32:47], v[88:91], v[246:249], v[32:47]
	s_waitcnt lgkmcnt(4)
	v_mfma_f32_32x32x16_f16 v[16:31], v[92:95], v[246:249], v[16:31]
	s_waitcnt lgkmcnt(3)
	v_mfma_f32_32x32x16_f16 v[64:79], v[96:99], v[8:11], v[64:79]
	s_waitcnt lgkmcnt(2)
	v_mfma_f32_32x32x16_f16 v[48:63], v[100:103], v[8:11], v[48:63]
	s_waitcnt lgkmcnt(1)
	v_mfma_f32_32x32x16_f16 v[32:47], v[104:107], v[8:11], v[32:47]
	s_waitcnt lgkmcnt(0)
	v_mfma_f32_32x32x16_f16 v[16:31], v[108:111], v[8:11], v[16:31]
	s_branch .Lattn_tile_end

; #define LAS __attribute__((address_space(3)))
; __device__ __forceinline__ unsigned pk_bf16(float lo, float hi) { f32x2 v; v.x = lo; v.y = hi; const bf16x2_t b = __builtin_convertvector(v, bf16x2_t); return __builtin_bit_cast(unsigned, b); }
; __device__ __forceinline__ void phase_gla(const Frame& F, int l, int gi, int ng, bool last, unsigned* cw) {
;     ...
;             { const int cb = chunk_base(s), i0 = it * 32 + 4 * hh; const long rs = dir ? -(long)DM : (long)DM;
;               f16* ob = Oout + (size_t)(cb + (dir ? 63 - i0 : i0)) * DM + h * 256 + sl * 128 + et * 32 + r32;
; #pragma unroll
;               for (int e = 0; e < 16; ++e) ob[((e & 3) + 8 * (e >> 2)) * rs] = (f16)oacc[e]; }
; #pragma unroll
;             for (int q = 0; q < 2; ++q) {
; #pragma unroll
;                 for (int g4 = 0; g4 < 4; ++g4) { const f32x4 ev = *(const LAS f32x4*)(lds + GL_EB + (dt * 32 + g4 * 8 + hh * 4) * 4);
; #pragma unroll
;                     for (int e = 0; e < 4; ++e) Sacc[q][g4 * 4 + e] *= ev[e]; }
; #pragma unroll
;                 for (int ks = 0; ks < 4; ++ks) {
;                     const s16x8 a = *(const LAS s16x8*)(lds + GL_KT + ((dt * 32 + r32) * 72 + ks * 16 + hh * 8) * 2);
;                     const s16x8 bb = *(const LAS s16x8*)(lds + GL_VT + (((e2 + q) * 32 + r32) * 72 + ks * 16 + hh * 8) * 2);
;                     Sacc[q] = __builtin_amdgcn_mfma_f32_32x32x16_bf16(a, bb, Sacc[q], 0, 0, 0); }
; #pragma unroll
;                 for (int g4 = 0; g4 < 4; ++g4)
;                     *(LAS u32x2*)(lds + GL_ST + (((e2 + q) * 32 + r32) * 136 + dt * 32 + g4 * 8 + hh * 4) * 2) = (u32x2){pk_bf16(Sacc[q][g4 * 4], Sacc[q][g4 * 4 + 1]), pk_bf16(Sacc[q][g4 * 4 + 2], Sacc[q][g4 * 4 + 3])};
;             }
;             __syncthreads();
.LBB0_643:
	s_waitcnt lgkmcnt(7)
	v_pk_mul_f32 v[2:3], v[2:3], v[230:231]
	v_pk_mul_f32 v[4:5], v[4:5], v[232:233]
	v_pk_mul_f32 v[18:19], v[18:19], v[230:231]
	v_pk_mul_f32 v[20:21], v[20:21], v[232:233]
	s_waitcnt lgkmcnt(6)
	v_pk_mul_f32 v[6:7], v[6:7], v[242:243]
	v_pk_mul_f32 v[8:9], v[8:9], v[244:245]
	v_pk_mul_f32 v[22:23], v[22:23], v[242:243]
	v_pk_mul_f32 v[24:25], v[24:25], v[244:245]
	s_waitcnt lgkmcnt(5)
	v_pk_mul_f32 v[10:11], v[10:11], v[246:247]
	v_pk_mul_f32 v[12:13], v[12:13], v[248:249]
	v_pk_mul_f32 v[26:27], v[26:27], v[246:247]
	v_pk_mul_f32 v[28:29], v[28:29], v[248:249]
	s_waitcnt lgkmcnt(4)
	v_pk_mul_f32 v[14:15], v[14:15], v[62:63]
	v_pk_mul_f32 v[16:17], v[16:17], v[64:65]
	v_pk_mul_f32 v[30:31], v[30:31], v[62:63]
	v_pk_mul_f32 v[32:33], v[32:33], v[64:65]
	v_add_u32_e32 v184, s0, v107
	v_readlane_b32 s0, v254, 16
	v_ashrrev_i32_e32 v185, 31, v184
	v_lshlrev_b64 v[184:185], 11, v[184:185]
	v_lshl_add_u64 v[184:185], v[112:113], 0, v[184:185]
	v_add_u32_e32 v189, s0, v130
	v_readlane_b32 s0, v254, 17
	ds_read_b128 v[192:195], v189
	ds_read_b128 v[200:203], v173
	ds_read_b128 v[214:217], v189 offset:32
	ds_read_b128 v[218:221], v173 offset:32
	ds_read_b128 v[222:225], v189 offset:64
	ds_read_b128 v[226:229], v173 offset:64
	ds_read_b128 v[230:233], v189 offset:96
	ds_read_b128 v[242:245], v173 offset:96
	v_cvt_f16_f32_e32 v188, v34
	global_store_short v[184:185], v188, off
	v_lshl_add_u64 v[186:187], s[8:9], 1, v[184:185]
	v_cvt_f16_f32_e32 v190, v35
	global_store_short v[186:187], v190, off
	v_lshl_add_u64 v[186:187], v[186:187], 0, s[10:11]
	v_cvt_f16_f32_e32 v188, v36
	global_store_short v[186:187], v188, off
	v_lshl_add_u64 v[186:187], v[186:187], 0, s[10:11]
	v_cvt_f16_f32_e32 v190, v37
	global_store_short v[186:187], v190, off
	v_lshl_add_u64 v[186:187], v[186:187], 0, s[86:87]
	s_waitcnt lgkmcnt(7)
	v_mfma_f32_32x32x16_bf16 v[2:17], v[50:53], v[192:195], v[2:17]
	v_cvt_f16_f32_e32 v188, v38
	global_store_short v[186:187], v188, off
	v_lshl_add_u64 v[186:187], v[186:187], 0, s[10:11]
	v_cvt_f16_f32_e32 v190, v39
	global_store_short v[186:187], v190, off
	s_waitcnt lgkmcnt(6)
	v_mfma_f32_32x32x16_bf16 v[18:33], v[50:53], v[200:203], v[18:33]
	v_lshl_add_u64 v[186:187], v[186:187], 0, s[10:11]
	v_cvt_f16_f32_e32 v188, v40
	global_store_short v[186:187], v188, off
	v_lshl_add_u64 v[186:187], v[186:187], 0, s[10:11]
	v_cvt_f16_f32_e32 v190, v41
	s_waitcnt lgkmcnt(5)
	v_mfma_f32_32x32x16_bf16 v[2:17], v[54:57], v[214:217], v[2:17]
	global_store_short v[186:187], v190, off
	v_lshl_add_u64 v[186:187], v[186:187], 0, s[86:87]
	v_cvt_f16_f32_e32 v188, v42
	global_store_short v[186:187], v188, off
	v_lshl_add_u64 v[186:187], v[186:187], 0, s[10:11]
	s_waitcnt lgkmcnt(4)
	v_mfma_f32_32x32x16_bf16 v[18:33], v[54:57], v[218:221], v[18:33]
	v_cvt_f16_f32_e32 v190, v43
	global_store_short v[186:187], v190, off
	v_lshl_add_u64 v[186:187], v[186:187], 0, s[10:11]
	v_cvt_f16_f32_e32 v188, v44
	global_store_short v[186:187], v188, off
	s_waitcnt lgkmcnt(3)
	v_mfma_f32_32x32x16_bf16 v[2:17], v[58:61], v[222:225], v[2:17]
	v_lshl_add_u64 v[186:187], v[186:187], 0, s[10:11]
	v_cvt_f16_f32_e32 v190, v45
	global_store_short v[186:187], v190, off
	v_lshl_add_u64 v[186:187], v[186:187], 0, s[86:87]
	v_cvt_f16_f32_e32 v188, v46
	s_waitcnt lgkmcnt(2)
	v_mfma_f32_32x32x16_bf16 v[18:33], v[58:61], v[226:229], v[18:33]
	global_store_short v[186:187], v188, off
	v_lshl_add_u64 v[186:187], v[186:187], 0, s[10:11]
	v_cvt_f16_f32_e32 v190, v47
	global_store_short v[186:187], v190, off
	v_lshl_add_u64 v[186:187], v[186:187], 0, s[10:11]
	s_waitcnt lgkmcnt(1)
	v_mfma_f32_32x32x16_bf16 v[2:17], v[180:183], v[230:233], v[2:17]
	v_cvt_f16_f32_e32 v188, v48
	global_store_short v[186:187], v188, off
	v_lshl_add_u64 v[186:187], v[186:187], 0, s[10:11]
	v_cvt_f16_f32_e32 v190, v49
	global_store_short v[186:187], v190, off
	s_waitcnt lgkmcnt(0)
	v_mfma_f32_32x32x16_bf16 v[18:33], v[180:183], v[242:245], v[18:33]
	v_add_u32_e32 v36, s33, v131
	s_nop 10
	v_cvt_pk_bf16_f32 v34, v2, v3
	v_cvt_pk_bf16_f32 v35, v4, v5
	ds_write_b64 v36, v[34:35]
	v_cvt_pk_bf16_f32 v34, v6, v7
	v_cvt_pk_bf16_f32 v35, v8, v9
	v_add_u32_e32 v36, s0, v131
	ds_write_b64 v36, v[34:35]
	v_cvt_pk_bf16_f32 v34, v10, v11
	v_cvt_pk_bf16_f32 v35, v12, v13
	v_add_u32_e32 v36, s95, v131
	ds_write_b64 v36, v[34:35]
	v_cvt_pk_bf16_f32 v34, v14, v15
	v_cvt_pk_bf16_f32 v35, v16, v17
	v_add_u32_e32 v36, s89, v131
	ds_write_b64 v36, v[34:35]
	v_add_u32_e32 v36, s33, v132
	v_cvt_pk_bf16_f32 v34, v18, v19
	v_cvt_pk_bf16_f32 v35, v20, v21
	ds_write_b64 v36, v[34:35]
	v_cvt_pk_bf16_f32 v34, v22, v23
	v_cvt_pk_bf16_f32 v35, v24, v25
	v_add_u32_e32 v36, s0, v132
	ds_write_b64 v36, v[34:35]
	v_cvt_pk_bf16_f32 v34, v26, v27
	v_cvt_pk_bf16_f32 v35, v28, v29
	v_add_u32_e32 v36, s95, v132
	ds_write_b64 v36, v[34:35]
	v_cvt_pk_bf16_f32 v34, v30, v31
	v_cvt_pk_bf16_f32 v35, v32, v33
	v_add_u32_e32 v36, s89, v132
	ds_write_b64 v36, v[34:35]
	s_add_i32 s37, s37, -1
	s_add_i32 s7, s7, 1
	s_cmp_eq_u32 s7, 64
	s_waitcnt lgkmcnt(0)
	s_barrier
	s_cbranch_scc1 .LBB0_666
; #define LAS __attribute__((address_space(3)))
; __device__ __forceinline__ unsigned pk_bf16(float lo, float hi) { f32x2 v; v.x = lo; v.y = hi; const bf16x2_t b = __builtin_convertvector(v, bf16x2_t); return __builtin_bit_cast(unsigned, b); }
; __device__ __forceinline__ void phase_gla(const Frame& F, int l, int gi, int ng, bool last, unsigned* cw) {
;     ...
;             *(LAS u32x4*)(lds + GL_RQ + (li * 136 + ls * 16) * 2) = pq0; *(LAS u32x4*)(lds + GL_RQ + (li * 136 + ls * 16 + 8) * 2) = pq1;
;             *(LAS u32x4*)(lds + GL_RK + (li * 136 + ls * 16) * 2) = pk0; *(LAS u32x4*)(lds + GL_RK + (li * 136 + ls * 16 + 8) * 2) = pk1;
;             *(LAS unsigned*)(lds + GL_LR + (li * 16 + ls * 2) * 2) = pk_f16(pg.x, pg.y);
;             { const f16x8 va = __builtin_bit_cast(f16x8, pv0), vb = __builtin_bit_cast(f16x8, pv1);
; #pragma unroll
;               for (int e = 0; e < 8; e += 2) { const unsigned pa = pk_bf16((float)va[e], (float)va[e + 1]), pb = pk_bf16((float)vb[e], (float)vb[e + 1]);
;                   *(LAS unsigned short*)(lds + GL_VT + ((vs * 16 + e) * 72 + vi) * 2) = (unsigned short)(pa & 0xffffu);
;                   *(LAS unsigned short*)(lds + GL_VT + ((vs * 16 + e + 1) * 72 + vi) * 2) = (unsigned short)(pa >> 16);
;                   *(LAS unsigned short*)(lds + GL_VT + ((vs * 16 + 8 + e) * 72 + vi) * 2) = (unsigned short)(pb & 0xffffu);
;                   *(LAS unsigned short*)(lds + GL_VT + ((vs * 16 + 8 + e + 1) * 72 + vi) * 2) = (unsigned short)(pb >> 16); } }
;             __syncthreads();
;             if (s + 1 < 68) GLA_LOAD(s + 1);
;             { const f16x8 ga = *(const LAS f16x8*)(lds + GL_LR + ((w >> 2) * 32 + r32) * 32 + hh * 16);
;               f32x16 la;
; #pragma unroll
;               for (int e = 0; e < 16; ++e) la[e] = 0.f;
;               la = __builtin_amdgcn_mfma_f32_32x32x16_f16(ga, gwf, la, 0, 0, 0);
.LBB0_644:
	s_waitcnt vmcnt(0)
	v_cvt_pk_f16_f32 v34, v118, v119
	ds_write_b128 v137, v[70:73]
	ds_write_b128 v137, v[74:77] offset:16
	ds_write_b128 v137, v[82:85] offset:17408
	ds_write_b128 v137, v[78:81] offset:17424
	ds_write_b32 v138, v34 offset:34816
	v_cvt_f32_f16_sdwa v34, v86 dst_sel:DWORD dst_unused:UNUSED_PAD src0_sel:WORD_1
	v_cvt_f32_f16_e32 v35, v86
	v_cvt_f32_f16_e32 v36, v90
	s_add_i32 s14, s7, 4
	s_cmp_eq_u32 s7, 63
	v_cvt_pk_bf16_f32 v34, v35, v34
	v_cvt_f32_f16_sdwa v35, v90 dst_sel:DWORD dst_unused:UNUSED_PAD src0_sel:WORD_1
	v_cvt_pk_bf16_f32 v35, v36, v35
	ds_write_b16 v139, v34
	ds_write_b16_d16_hi v140, v34
	ds_write_b16 v141, v35
	ds_write_b16_d16_hi v142, v35
	v_cvt_f32_f16_sdwa v34, v87 dst_sel:DWORD dst_unused:UNUSED_PAD src0_sel:WORD_1
	v_cvt_f32_f16_e32 v35, v87
	v_cvt_f32_f16_e32 v36, v91
	v_cvt_pk_bf16_f32 v34, v35, v34
	v_cvt_f32_f16_sdwa v35, v91 dst_sel:DWORD dst_unused:UNUSED_PAD src0_sel:WORD_1
	v_cvt_pk_bf16_f32 v35, v36, v35
	ds_write_b16 v143, v34
	ds_write_b16_d16_hi v144, v34
	ds_write_b16 v145, v35
	ds_write_b16_d16_hi v146, v35
	v_cvt_f32_f16_sdwa v34, v88 dst_sel:DWORD dst_unused:UNUSED_PAD src0_sel:WORD_1
	v_cvt_f32_f16_e32 v35, v88
	v_cvt_f32_f16_e32 v36, v92
	v_cvt_pk_bf16_f32 v34, v35, v34
	v_cvt_f32_f16_sdwa v35, v92 dst_sel:DWORD dst_unused:UNUSED_PAD src0_sel:WORD_1
	v_cvt_pk_bf16_f32 v35, v36, v35
	ds_write_b16 v147, v34
	ds_write_b16_d16_hi v148, v34
	ds_write_b16 v149, v35
	ds_write_b16_d16_hi v150, v35
	v_cvt_f32_f16_sdwa v34, v89 dst_sel:DWORD dst_unused:UNUSED_PAD src0_sel:WORD_1
	v_cvt_f32_f16_e32 v35, v89
	v_cvt_f32_f16_e32 v36, v93
	v_cvt_pk_bf16_f32 v34, v35, v34
	v_cvt_f32_f16_sdwa v35, v93 dst_sel:DWORD dst_unused:UNUSED_PAD src0_sel:WORD_1
	v_cvt_pk_bf16_f32 v35, v36, v35
	ds_write_b16 v151, v34
	ds_write_b16_d16_hi v152, v34
	ds_write_b16 v153, v35
	ds_write_b16_d16_hi v154, v35
	s_waitcnt lgkmcnt(0)
	s_barrier
	ds_read_b128 v[34:37], v155 offset:34816
	s_waitcnt lgkmcnt(0)
	v_mfma_f32_32x32x16_f16 v[34:49], v[34:37], v[66:69], 0
	s_cbranch_scc1 .Lgla_s1_skip
	s_cmp_gt_u32 s14, 2
	s_cselect_b64 s[2:3], -1, 0
	s_mov_b64 s[12:13], -1
	s_and_b64 vcc, exec, s[2:3]
	s_cbranch_vccz .LBB0_647
	s_add_i32 s0, s7, 1
	s_and_b64 s[12:13], s[84:85], exec
	s_cselect_b32 s0, s0, s37
	s_mov_b64 s[12:13], 0

.LBB0_649:
	s_lshl_b32 s0, s0, 6
	s_add_i32 s0, s0, s12
	v_add_u32_e32 v184, s0, v174
	v_mov_b64_e32 v[186:187], s[22:23]
	v_mad_i64_i32 v[186:187], s[12:13], v184, s1, v[186:187]
	v_mov_b32_e32 v111, v1
	v_lshl_add_u64 v[186:187], s[34:35], 1, v[186:187]
	v_lshl_add_u64 v[186:187], v[186:187], 0, v[110:111]
	v_add_co_u32_e32 v190, vcc, 0x1000, v186
	s_mov_b64 s[12:13], 0x1800
	s_nop 0
	v_addc_co_u32_e32 v191, vcc, 0, v187, vcc
	v_lshl_add_u64 v[188:189], v[186:187], 0, s[12:13]
	global_load_dwordx4 v[70:73], v[190:191], off offset:2048
	global_load_dwordx4 v[74:77], v[188:189], off offset:16
	global_load_dwordx4 v[78:81], v[186:187], off offset:1040
	global_load_dwordx4 v[82:85], v[186:187], off offset:1024
	s_mov_b64 s[12:13], -1
	s_and_b64 vcc, exec, s[2:3]
	s_cbranch_vccz .LBB0_651
	s_add_i32 s0, s7, 1
	s_and_b64 s[2:3], s[84:85], exec
	s_cselect_b32 s2, s0, s37
	s_mov_b64 s[12:13], 0

; #define LAS __attribute__((address_space(3)))
; __device__ __forceinline__ void phase_gla(const Frame& F, int l, int gi, int ng, bool last, unsigned* cw) {
;     ...
; #pragma unroll
;               for (int e = 0; e < 16; ++e) { const int i = (w >> 2) * 32 + (e & 3) + 8 * (e >> 2) + 4 * hh; const float lg = la[e] + gbv;
;                   ((LAS float*)(lds + GL_QT))[i * 128 + (w & 3) * 32 + r32] = (fminf(lg, 0.f) * 1.4426950408889634f - __builtin_amdgcn_logf(1.0f + __builtin_amdgcn_exp2f(fabsf(lg) * -1.4426950408889634f))) * (1.0f / 16.0f); } }
;             __syncthreads();
;             float bl[16]; float cum = 0.f;
; #pragma unroll
;             for (int ii = 0; ii < 16; ++ii) { cum += ((const LAS float*)(lds + GL_QT))[(tg * 16 + ii) * 128 + d]; bl[ii] = cum; }
;             ((LAS float*)(lds + GL_PS))[tg * 128 + d] = cum;
;             __syncthreads();
.LBB0_653:
	s_lshl_b32 s0, s2, 6
	v_ashrrev_i32_e32 v185, 31, v184
	s_add_i32 s0, s0, s3
	v_add_u32_e32 v186, s0, v175
	v_lshlrev_b64 v[184:185], 7, v[184:185]
	v_mad_i64_i32 v[186:187], s[2:3], v186, s1, v[116:117]
	v_lshl_add_u64 v[184:185], v[114:115], 0, v[184:185]
	global_load_dwordx4 v[86:89], v[186:187], off offset:2048
	global_load_dwordx4 v[90:93], v[186:187], off offset:2064
	global_load_dwordx2 v[118:119], v[184:185], off
.LBB0_654:
	v_add_u32_e32 v50, s39, v122
	v_add_f32_e32 v34, v103, v34
	v_add_f32_e32 v35, v103, v35
	v_min_f32_e32 v51, 0, v34
	v_mul_f32_e64 v34, |v34|, s15
	v_min_f32_e32 v52, 0, v35
	v_mul_f32_e64 v35, |v35|, s15
	v_exp_f32_e32 v34, v34
	v_exp_f32_e32 v35, v35
	v_add_f32_e32 v36, v103, v36
	v_add_f32_e32 v37, v103, v37
	v_min_f32_e32 v53, 0, v36
	v_mul_f32_e64 v36, |v36|, s15
	v_mul_f32_e64 v54, |v37|, s15
	v_exp_f32_e32 v36, v36
	v_exp_f32_e32 v54, v54
	v_add_f32_e32 v34, 1.0, v34
	v_add_f32_e32 v35, 1.0, v35
	v_log_f32_e32 v34, v34
	v_log_f32_e32 v35, v35
	v_add_f32_e32 v36, 1.0, v36
	v_add_f32_e32 v54, 1.0, v54
	v_log_f32_e32 v36, v36
	v_log_f32_e32 v54, v54
	v_fma_f32 v34, v51, s82, -v34
	v_fma_f32 v35, v52, s82, -v35
	v_mul_f32_e32 v34, 0x3d800000, v34
	v_mul_f32_e32 v35, 0x3d800000, v35
	ds_write2st64_b32 v50, v34, v35 offset0:152 offset1:154
	v_min_f32_e32 v35, 0, v37
	v_fma_f32 v34, v53, s82, -v36
	v_fma_f32 v35, v35, s82, -v54
	v_mul_f32_e32 v34, 0x3d800000, v34
	v_mul_f32_e32 v35, 0x3d800000, v35
	ds_write2st64_b32 v50, v34, v35 offset0:156 offset1:158
	v_add_f32_e32 v34, v103, v38
	v_mul_f32_e64 v35, |v34|, s15
	v_add_f32_e32 v36, v103, v39
	v_exp_f32_e32 v35, v35
	v_mul_f32_e64 v37, |v36|, s15
	v_exp_f32_e32 v37, v37
	v_min_f32_e32 v34, 0, v34
	v_add_f32_e32 v35, 1.0, v35
	v_log_f32_e32 v35, v35
	v_add_f32_e32 v37, 1.0, v37
	v_log_f32_e32 v37, v37
	v_fma_f32 v34, v34, s82, -v35
	v_min_f32_e32 v35, 0, v36
	v_fma_f32 v35, v35, s82, -v37
	v_mul_f32_e32 v34, 0x3d800000, v34
	v_mul_f32_e32 v35, 0x3d800000, v35
	ds_write2st64_b32 v50, v34, v35 offset0:168 offset1:170
	v_add_f32_e32 v34, v103, v40
	v_mul_f32_e64 v35, |v34|, s15
	v_add_f32_e32 v36, v103, v41
	v_exp_f32_e32 v35, v35
	v_mul_f32_e64 v37, |v36|, s15
	v_exp_f32_e32 v37, v37
	v_min_f32_e32 v34, 0, v34
	v_add_f32_e32 v35, 1.0, v35
	v_log_f32_e32 v35, v35
	v_add_f32_e32 v37, 1.0, v37
	v_log_f32_e32 v37, v37
	v_fma_f32 v34, v34, s82, -v35
	v_min_f32_e32 v35, 0, v36
	v_fma_f32 v35, v35, s82, -v37
	v_mul_f32_e32 v34, 0x3d800000, v34
	v_mul_f32_e32 v35, 0x3d800000, v35
	ds_write2st64_b32 v50, v34, v35 offset0:172 offset1:174
	v_add_f32_e32 v34, v103, v42
	v_mul_f32_e64 v35, |v34|, s15
	v_add_f32_e32 v36, v103, v43
	v_exp_f32_e32 v35, v35
	v_mul_f32_e64 v37, |v36|, s15
	v_exp_f32_e32 v37, v37
	v_min_f32_e32 v34, 0, v34
	v_add_f32_e32 v35, 1.0, v35
	v_log_f32_e32 v35, v35
	v_add_f32_e32 v37, 1.0, v37
	v_log_f32_e32 v37, v37
	v_fma_f32 v34, v34, s82, -v35
	v_min_f32_e32 v35, 0, v36
	v_add_f32_e32 v36, v103, v44
	v_fma_f32 v35, v35, s82, -v37
	v_mul_f32_e64 v37, |v36|, s15
	v_exp_f32_e32 v37, v37
	v_mul_f32_e32 v34, 0x3d800000, v34
	v_mul_f32_e32 v35, 0x3d800000, v35
	ds_write2st64_b32 v50, v34, v35 offset0:184 offset1:186
	v_min_f32_e32 v34, 0, v36
	v_add_f32_e32 v36, v103, v45
	v_add_f32_e32 v35, 1.0, v37
	v_mul_f32_e64 v37, |v36|, s15
	v_log_f32_e32 v35, v35
	v_exp_f32_e32 v37, v37
	v_fma_f32 v34, v34, s82, -v35
	v_min_f32_e32 v35, 0, v36
	v_add_f32_e32 v36, 1.0, v37
	v_log_f32_e32 v36, v36
	v_add_f32_e32 v37, v103, v46
	v_mul_f32_e64 v38, |v37|, s15
	v_mul_f32_e32 v34, 0x3d800000, v34
	v_fma_f32 v35, v35, s82, -v36
	v_exp_f32_e32 v38, v38
	v_mul_f32_e32 v35, 0x3d800000, v35
	ds_write2st64_b32 v50, v34, v35 offset0:188 offset1:190
	v_add_f32_e32 v35, v103, v47
	v_mul_f32_e64 v36, |v35|, s15
	v_exp_f32_e32 v36, v36
	v_add_f32_e32 v34, 1.0, v38
	v_log_f32_e32 v34, v34
	v_min_f32_e32 v37, 0, v37
	v_add_f32_e32 v36, 1.0, v36
	v_log_f32_e32 v36, v36
	v_fma_f32 v34, v37, s82, -v34
	v_mul_f32_e32 v34, 0x3d800000, v34
	v_add_u32_e32 v37, s92, v122
	ds_write_b32 v37, v34 offset:38912
	v_min_f32_e32 v34, 0, v35
	v_add_f32_e32 v35, v103, v48
	v_fma_f32 v34, v34, s82, -v36
	v_mul_f32_e64 v36, |v35|, s15
	v_exp_f32_e32 v36, v36
	v_mul_f32_e32 v34, 0x3d800000, v34
	v_add_u32_e32 v37, s93, v122
	ds_write_b32 v37, v34 offset:38912
	v_add_f32_e32 v34, 1.0, v36
	v_add_f32_e32 v36, v103, v49
	v_mul_f32_e64 v37, |v36|, s15
	v_log_f32_e32 v34, v34
	v_exp_f32_e32 v37, v37
	v_min_f32_e32 v35, 0, v35
	v_fma_f32 v34, v35, s82, -v34
	v_add_f32_e32 v35, 1.0, v37
	v_log_f32_e32 v35, v35
	v_mul_f32_e32 v34, 0x3d800000, v34
	v_add_u32_e32 v37, s90, v122
	ds_write_b32 v37, v34 offset:38912
	v_min_f32_e32 v34, 0, v36
	v_fma_f32 v34, v34, s82, -v35
	v_mul_f32_e32 v34, 0x3d800000, v34
	v_add_u32_e32 v35, s91, v122
	ds_write_b32 v35, v34 offset:38912
	s_waitcnt lgkmcnt(0)
	s_barrier
	ds_read2st64_b32 v[34:35], v123 offset0:152 offset1:154
	ds_read2st64_b32 v[36:37], v123 offset0:156 offset1:158
	ds_read2st64_b32 v[38:39], v123 offset0:160 offset1:162
	ds_read2st64_b32 v[40:41], v123 offset0:176 offset1:178
	s_waitcnt lgkmcnt(3)
	v_add_f32_e32 v55, 0, v34
	v_add_f32_e32 v54, v55, v35
	ds_read2st64_b32 v[34:35], v123 offset0:164 offset1:166
	s_waitcnt lgkmcnt(3)
	v_add_f32_e32 v53, v54, v36
	v_add_f32_e32 v52, v53, v37
	s_waitcnt lgkmcnt(2)
	v_add_f32_e32 v51, v52, v38
	ds_read2st64_b32 v[36:37], v123 offset0:168 offset1:170
	v_add_f32_e32 v50, v51, v39
	s_waitcnt lgkmcnt(1)
	v_add_f32_e32 v38, v50, v34
	v_add_f32_e32 v39, v38, v35
	ds_read2st64_b32 v[34:35], v123 offset0:172 offset1:174
	s_waitcnt lgkmcnt(1)
	v_add_f32_e32 v49, v39, v36
	v_add_f32_e32 v48, v49, v37
	ds_read2st64_b32 v[36:37], v123 offset0:180 offset1:182
	s_waitcnt lgkmcnt(1)
	v_add_f32_e32 v47, v48, v34
	v_add_f32_e32 v46, v47, v35
	v_add_f32_e32 v45, v46, v40
	v_add_f32_e32 v44, v45, v41
	s_waitcnt lgkmcnt(0)
	v_add_f32_e32 v40, v44, v36
	v_add_f32_e32 v41, v40, v37
	ds_write_b32 v124, v41
	s_waitcnt lgkmcnt(0)
	s_barrier
; #define LAS __attribute__((address_space(3)))
; __device__ __forceinline__ unsigned pk_bf16(float lo, float hi) { f32x2 v; v.x = lo; v.y = hi; const bf16x2_t b = __builtin_convertvector(v, bf16x2_t); return __builtin_bit_cast(unsigned, b); }
; __device__ __forceinline__ void phase_gla(const Frame& F, int l, int gi, int ng, bool last, unsigned* cw) {
;     ...
;             float off = 0.f, tot = 0.f;
; #pragma unroll
;             for (int t2 = 0; t2 < 4; ++t2) { const float pv2 = ((LAS float*)(lds + GL_PS))[t2 * 128 + d]; tot += pv2; if (t2 < tg) off += pv2; }
;             const float etot = __builtin_amdgcn_exp2f(tot);
;             if (tg == 0) ((LAS float*)(lds + GL_EB))[d] = etot;
;             { unsigned ktp[8];
; #pragma unroll
;               for (int ii = 0; ii < 16; ii += 2) {
;                   float kt2[2];
; #pragma unroll
;                   for (int e = 0; e < 2; ++e) { const int i = tg * 16 + ii + e; const float bi = off + bl[ii + e];
;                       const float qv = (float)*(const LAS f16*)(lds + GL_RQ + (i * 136 + d) * 2), kv = (float)*(const LAS f16*)(lds + GL_RK + (i * 136 + d) * 2);
;                       const float qt = qv * 0.08838834764831845f * __builtin_amdgcn_exp2f(bi), kh = kv * __builtin_amdgcn_exp2f(-bi); kt2[e] = kh * etot;
;                       *(LAS unsigned short*)(lds + GL_QT + (i * 136 + d) * 2) = (unsigned short)(pk_bf16(qt, qt) & 0xffffu);
;                       *(LAS unsigned short*)(lds + GL_KH + (i * 136 + d) * 2) = (unsigned short)(pk_bf16(kh, kh) & 0xffffu); }
;                   ktp[ii >> 1] = pk_bf16(kt2[0], kt2[1]); }
	ds_read2st64_b32 v[36:37], v125 offset1:2
	ds_read2st64_b32 v[34:35], v125 offset0:4 offset1:6
	s_waitcnt lgkmcnt(1)
	v_add_f32_e32 v36, 0, v36
	v_add_f32_e32 v42, v36, v37
	s_waitcnt lgkmcnt(0)
	v_add_f32_e32 v42, v42, v34
	v_add_f32_e32 v42, v42, v35
	v_exp_f32_e32 v42, v42
	s_and_saveexec_b64 s[2:3], s[40:41]
	ds_write_b32 v128, v42
	s_or_b64 exec, exec, s[2:3]
	v_cndmask_b32_e64 v36, 0, v36, s[42:43]
	v_add_f32_e32 v37, v37, v36
	v_cndmask_b32_e64 v36, v36, v37, s[44:45]
	ds_read_u16 v37, v129
	v_add_f32_e32 v34, v34, v36
	v_cndmask_b32_e64 v34, v36, v34, s[46:47]
	v_add_f32_e32 v35, v35, v34
	v_cndmask_b32_e64 v43, v34, v35, s[48:49]
	v_add_f32_e32 v34, v55, v43
	ds_read_u16 v55, v129 offset:17408
	s_waitcnt lgkmcnt(1)
	v_cvt_f32_f16_e32 v35, v37
	v_exp_f32_e32 v36, v34
	ds_read_u16 v37, v129 offset:17680
	v_exp_f32_e64 v34, -v34
	v_mul_f32_e32 v35, 0x3db504f3, v35
	v_mul_f32_e32 v35, v36, v35
	ds_read_u16 v36, v129 offset:272
	v_cvt_pk_bf16_f32 v56, v35, s0
	v_add_f32_e32 v35, v54, v43
	v_exp_f32_e32 v57, v35
	v_exp_f32_e64 v35, -v35
	s_waitcnt lgkmcnt(0)
	v_cvt_f32_f16_e32 v54, v36
	v_cvt_f32_f16_e32 v37, v37
	v_cvt_f32_f16_e32 v36, v55
	ds_read_u16 v55, v129 offset:17952
	v_mul_f32_e32 v54, 0x3db504f3, v54
	v_mul_f32_e32 v54, v57, v54
	v_pk_mul_f32 v[34:35], v[34:35], v[36:37]
	ds_write_b16 v129, v56 offset:38912
	v_cvt_pk_bf16_f32 v36, v34, s0
	ds_write_b16 v129, v36 offset:56320
	v_pk_mul_f32 v[36:37], v[42:43], v[34:35] op_sel_hi:[0,1]
	v_cvt_pk_bf16_f32 v34, v54, s0
	ds_read_u16 v54, v129 offset:544
	ds_write_b16 v129, v34 offset:39184
	v_cvt_pk_bf16_f32 v34, v35, s0
	v_add_f32_e32 v35, v53, v43
	ds_write_b16 v129, v34 offset:56592
	s_waitcnt lgkmcnt(2)
	v_cvt_f32_f16_e32 v53, v54
	v_exp_f32_e32 v54, v35
	v_cvt_pk_bf16_f32 v34, v36, v37
	v_add_f32_e32 v39, v39, v43
	v_mul_f32_e32 v36, 0x3db504f3, v53
	v_mul_f32_e32 v37, v54, v36
	ds_read_u16 v53, v129 offset:816
	ds_read_u16 v54, v129 offset:18224
	v_exp_f32_e64 v36, -v35
	v_cvt_pk_bf16_f32 v35, v37, s0
	v_add_f32_e32 v37, v52, v43
	s_waitcnt lgkmcnt(1)
	v_cvt_f32_f16_e32 v56, v53
	v_exp_f32_e32 v57, v37
	v_exp_f32_e64 v37, -v37
	s_waitcnt lgkmcnt(0)
	v_cvt_f32_f16_e32 v53, v54
	v_cvt_f32_f16_e32 v52, v55
	ds_write_b16 v129, v35 offset:39456
	v_mul_f32_e32 v35, 0x3db504f3, v56
	v_mul_f32_e32 v35, v57, v35
	v_pk_mul_f32 v[36:37], v[36:37], v[52:53]
	v_cvt_pk_bf16_f32 v35, v35, s0
	v_cvt_pk_bf16_f32 v52, v36, s0
	ds_write_b16 v129, v52 offset:56864
	v_pk_mul_f32 v[52:53], v[42:43], v[36:37] op_sel_hi:[0,1]
	ds_read_u16 v36, v129 offset:1088
	ds_write_b16 v129, v35 offset:39728
	v_cvt_pk_bf16_f32 v35, v37, s0
	ds_write_b16 v129, v35 offset:57136
	v_add_f32_e32 v37, v51, v43
	v_cvt_pk_bf16_f32 v35, v52, v53
	ds_read_u16 v52, v129 offset:18496
	ds_read_u16 v53, v129 offset:1360
	s_waitcnt lgkmcnt(4)
	v_cvt_f32_f16_e32 v36, v36
	v_exp_f32_e32 v51, v37
	v_add_f32_e32 v46, v46, v43
	v_add_f32_e32 v45, v45, v43
	v_mul_f32_e32 v36, 0x3db504f3, v36
	v_mul_f32_e32 v51, v51, v36
	v_cvt_pk_bf16_f32 v54, v51, s0
	ds_read_u16 v51, v129 offset:18768
	v_exp_f32_e64 v36, -v37
	v_add_f32_e32 v37, v50, v43
	s_waitcnt lgkmcnt(1)
	v_cvt_f32_f16_e32 v53, v53
	v_exp_f32_e32 v55, v37
	v_exp_f32_e64 v37, -v37
	v_cvt_f32_f16_e32 v50, v52
	s_waitcnt lgkmcnt(0)
	v_cvt_f32_f16_e32 v51, v51
	v_mul_f32_e32 v52, 0x3db504f3, v53
	v_mul_f32_e32 v52, v55, v52
	v_exp_f32_e32 v53, v39
	v_pk_mul_f32 v[36:37], v[36:37], v[50:51]
	v_exp_f32_e64 v39, -v39
	v_cvt_pk_bf16_f32 v50, v36, s0
	ds_write_b16 v129, v50 offset:57408
	v_pk_mul_f32 v[50:51], v[42:43], v[36:37] op_sel_hi:[0,1]
	v_cvt_pk_bf16_f32 v36, v52, s0
	ds_read_u16 v52, v129 offset:1632
	ds_write_b16 v129, v36 offset:40272
	v_cvt_pk_bf16_f32 v36, v37, s0
	ds_write_b16 v129, v36 offset:57680
	v_add_f32_e32 v37, v38, v43
	v_cvt_pk_bf16_f32 v36, v50, v51
	ds_read_u16 v50, v129 offset:19040
	s_waitcnt lgkmcnt(3)
	v_cvt_f32_f16_e32 v38, v52
	v_exp_f32_e32 v52, v37
	v_add_f32_e32 v44, v44, v43
	v_add_f32_e32 v41, v41, v43
	v_mul_f32_e32 v38, 0x3db504f3, v38
	v_mul_f32_e32 v51, v52, v38
	v_exp_f32_e64 v38, -v37
	v_cvt_pk_bf16_f32 v37, v51, s0
	ds_read_u16 v51, v129 offset:19312
	s_waitcnt lgkmcnt(1)
	v_cvt_f32_f16_e32 v50, v50
	ds_read_u16 v52, v129 offset:1904
	ds_write_b16 v129, v37 offset:40544
	ds_write_b16 v129, v54 offset:40000
	s_waitcnt lgkmcnt(3)
	v_cvt_f32_f16_e32 v51, v51
	s_mov_b64 s[2:3], -1
	s_and_b64 vcc, exec, s[26:27]
	v_pk_mul_f32 v[38:39], v[38:39], v[50:51]
	s_nop 0
	v_cvt_pk_bf16_f32 v50, v38, s0
	ds_write_b16 v129, v50 offset:57952
	v_pk_mul_f32 v[50:51], v[42:43], v[38:39] op_sel_hi:[0,1]
	ds_read_u16 v38, v129 offset:2176
	s_waitcnt lgkmcnt(4)
	v_cvt_f32_f16_e32 v52, v52
	v_mul_f32_e32 v37, 0x3db504f3, v52
	v_mul_f32_e32 v37, v53, v37
	v_cvt_pk_bf16_f32 v37, v37, s0
	ds_write_b16 v129, v37 offset:40816
	v_cvt_pk_bf16_f32 v37, v39, s0
	v_add_f32_e32 v39, v49, v43
	s_waitcnt lgkmcnt(1)
	v_cvt_f32_f16_e32 v38, v38
	v_exp_f32_e32 v49, v39
	ds_write_b16 v129, v37 offset:58224
	v_cvt_pk_bf16_f32 v37, v50, v51
	v_mul_f32_e32 v38, 0x3db504f3, v38
	v_mul_f32_e32 v49, v49, v38
	ds_read_u16 v50, v129 offset:19584
	v_cvt_pk_bf16_f32 v52, v49, s0
	ds_read_u16 v49, v129 offset:19856
	ds_read_u16 v51, v129 offset:2448
	v_exp_f32_e64 v38, -v39
	v_add_f32_e32 v39, v48, v43
	v_exp_f32_e32 v53, v39
	v_exp_f32_e64 v39, -v39
	s_waitcnt lgkmcnt(0)
; #define LAS __attribute__((address_space(3)))
; __device__ __forceinline__ void phase_gla(const Frame& F, int l, int gi, int ng, bool last, unsigned* cw) {
;     ...
;                   for (int e = 0; e < 2; ++e) { const int i = tg * 16 + ii + e; const float bi = off + bl[ii + e];
;                       const float qv = (float)*(const LAS f16*)(lds + GL_RQ + (i * 136 + d) * 2), kv = (float)*(const LAS f16*)(lds + GL_RK + (i * 136 + d) * 2);
;                       const float qt = qv * 0.08838834764831845f * __builtin_amdgcn_exp2f(bi), kh = kv * __builtin_amdgcn_exp2f(-bi); kt2[e] = kh * etot;
;                       *(LAS unsigned short*)(lds + GL_QT + (i * 136 + d) * 2) = (unsigned short)(pk_bf16(qt, qt) & 0xffffu);
;                       *(LAS unsigned short*)(lds + GL_KH + (i * 136 + d) * 2) = (unsigned short)(pk_bf16(kh, kh) & 0xffffu); }
;                   ktp[ii >> 1] = pk_bf16(kt2[0], kt2[1]); }
;               *(LAS u32x4*)(lds + GL_KT + (d * 72 + tg * 16) * 2) = (u32x4){ktp[0], ktp[1], ktp[2], ktp[3]};
;               *(LAS u32x4*)(lds + GL_KT + (d * 72 + tg * 16 + 8) * 2) = (u32x4){ktp[4], ktp[5], ktp[6], ktp[7]}; }
;             __syncthreads();
;             f32x16 oacc;
; #pragma unroll
;             for (int e = 0; e < 16; ++e) oacc[e] = 0.f;
; #pragma unroll
;             for (int ks = 0; ks < 8; ++ks) {
;                 const s16x8 a = *(const LAS s16x8*)(lds + GL_QT + ((it * 32 + r32) * 136 + ks * 16 + hh * 8) * 2);
;                 const s16x8 bb = *(const LAS s16x8*)(lds + GL_ST + ((et * 32 + r32) * 136 + ks * 16 + hh * 8) * 2);
;                 oacc = __builtin_amdgcn_mfma_f32_32x32x16_bf16(a, bb, oacc, 0, 0, 0); }
;             if (w >= 4 && w < 7) {
;                 const int jt = (w == 6) ? 1 : 0, it2 = (w == 4) ? 0 : 1;
;                 f32x16 aacc;
; #pragma unroll
;                 for (int e = 0; e < 16; ++e) aacc[e] = 0.f;
; #pragma unroll
;                 for (int ks = 0; ks < 8; ++ks) {
;                     const s16x8 a = *(const LAS s16x8*)(lds + GL_KH + ((jt * 32 + r32) * 136 + ks * 16 + hh * 8) * 2);
;                     const s16x8 bb = *(const LAS s16x8*)(lds + GL_QT + ((it2 * 32 + r32) * 136 + ks * 16 + hh * 8) * 2);
;                     aacc = __builtin_amdgcn_mfma_f32_32x32x16_bf16(a, bb, aacc, 0, 0, 0); }
;                 const int i = it2 * 32 + r32;
; #pragma unroll
	v_cvt_f32_f16_e32 v51, v51
	v_cvt_f32_f16_e32 v48, v50
	v_cvt_f32_f16_e32 v49, v49
	ds_write_b16 v129, v52 offset:41088
	v_mul_f32_e32 v50, 0x3db504f3, v51
	v_mul_f32_e32 v50, v53, v50
	v_pk_mul_f32 v[38:39], v[38:39], v[48:49]
	ds_read_u16 v51, v129 offset:20128
	v_cvt_pk_bf16_f32 v48, v38, s0
	ds_write_b16 v129, v48 offset:58496
	v_pk_mul_f32 v[48:49], v[42:43], v[38:39] op_sel_hi:[0,1]
	v_cvt_pk_bf16_f32 v38, v50, s0
	ds_read_u16 v50, v129 offset:2720
	ds_write_b16 v129, v38 offset:41360
	v_cvt_pk_bf16_f32 v38, v39, s0
	ds_write_b16 v129, v38 offset:58768
	v_add_f32_e32 v39, v47, v43
	v_cvt_pk_bf16_f32 v38, v48, v49
	ds_read_u16 v49, v129 offset:2992
	s_waitcnt lgkmcnt(3)
	v_cvt_f32_f16_e32 v47, v50
	v_exp_f32_e32 v50, v39
	v_exp_f32_e64 v48, -v39
	v_exp_f32_e32 v52, v46
	v_mul_f32_e32 v47, 0x3db504f3, v47
	v_mul_f32_e32 v47, v50, v47
	v_cvt_pk_bf16_f32 v39, v47, s0
	ds_read_u16 v47, v129 offset:20400
	s_waitcnt lgkmcnt(1)
	v_cvt_f32_f16_e32 v50, v49
	v_exp_f32_e64 v49, -v46
	v_cvt_f32_f16_e32 v46, v51
	ds_write_b16 v129, v39 offset:41632
	s_waitcnt lgkmcnt(1)
	v_cvt_f32_f16_e32 v47, v47
	v_mul_f32_e32 v39, 0x3db504f3, v50
	v_mul_f32_e32 v39, v52, v39
	v_cvt_pk_bf16_f32 v39, v39, s0
	v_pk_mul_f32 v[46:47], v[48:49], v[46:47]
	ds_write_b16 v129, v39 offset:41904
	v_cvt_pk_bf16_f32 v48, v46, s0
	ds_write_b16 v129, v48 offset:59040
	v_pk_mul_f32 v[48:49], v[42:43], v[46:47] op_sel_hi:[0,1]
	ds_read_u16 v46, v129 offset:3264
	v_cvt_pk_bf16_f32 v39, v47, s0
	ds_write_b16 v129, v39 offset:59312
	v_cvt_pk_bf16_f32 v39, v48, v49
	ds_read_u16 v48, v129 offset:20672
	ds_read_u16 v49, v129 offset:3536
	s_waitcnt lgkmcnt(3)
	v_cvt_f32_f16_e32 v46, v46
	v_exp_f32_e32 v47, v45
	v_exp_f32_e32 v51, v44
	v_mul_f32_e32 v46, 0x3db504f3, v46
	v_mul_f32_e32 v47, v47, v46
	v_exp_f32_e64 v46, -v45
	ds_read_u16 v45, v129 offset:20944
	v_cvt_pk_bf16_f32 v50, v47, s0
	s_waitcnt lgkmcnt(1)
	v_cvt_f32_f16_e32 v49, v49
	v_exp_f32_e64 v47, -v44
	v_cvt_f32_f16_e32 v44, v48
	s_waitcnt lgkmcnt(0)
	v_cvt_f32_f16_e32 v45, v45
	v_mul_f32_e32 v48, 0x3db504f3, v49
	v_mul_f32_e32 v48, v51, v48
	ds_write_b16 v129, v50 offset:42176
	v_pk_mul_f32 v[44:45], v[46:47], v[44:45]
	v_exp_f32_e32 v50, v41
	v_cvt_pk_bf16_f32 v46, v44, s0
	ds_write_b16 v129, v46 offset:59584
	v_pk_mul_f32 v[46:47], v[42:43], v[44:45] op_sel_hi:[0,1]
	v_cvt_pk_bf16_f32 v44, v48, s0
	ds_read_u16 v48, v129 offset:3808
	ds_write_b16 v129, v44 offset:42448
	v_cvt_pk_bf16_f32 v44, v45, s0
	ds_write_b16 v129, v44 offset:59856
	v_add_f32_e32 v44, v40, v43
	v_cvt_pk_bf16_f32 v40, v46, v47
	ds_read_u16 v46, v129 offset:21216
	ds_read_u16 v43, v129 offset:21488
	ds_read_u16 v47, v129 offset:4080
	s_waitcnt lgkmcnt(5)
	v_cvt_f32_f16_e32 v45, v48
	v_exp_f32_e32 v48, v44
	v_exp_f32_e64 v44, -v44
	s_waitcnt lgkmcnt(2)
	v_cvt_f32_f16_e32 v46, v46
	v_mul_f32_e32 v45, 0x3db504f3, v45
	v_mul_f32_e32 v45, v48, v45
	s_waitcnt lgkmcnt(0)
	v_cvt_f32_f16_e32 v49, v47
	v_cvt_pk_bf16_f32 v48, v45, s0
	v_exp_f32_e64 v45, -v41
	v_cvt_f32_f16_e32 v47, v43
	v_mul_f32_e32 v41, 0x3db504f3, v49
	v_mul_f32_e32 v41, v50, v41
	v_cvt_pk_bf16_f32 v41, v41, s0
	v_pk_mul_f32 v[44:45], v[44:45], v[46:47]
	ds_write_b16 v129, v41 offset:42992
	v_cvt_pk_bf16_f32 v43, v44, s0
	ds_write_b16 v129, v43 offset:60128
	v_pk_mul_f32 v[42:43], v[42:43], v[44:45] op_sel_hi:[0,1]
	v_cvt_pk_bf16_f32 v41, v45, s0
	ds_write_b16 v129, v41 offset:60400
	v_cvt_pk_bf16_f32 v41, v42, v43
	ds_write_b16 v129, v48 offset:42720
	ds_write_b128 v156, v[34:37]
	ds_write_b128 v156, v[38:41] offset:16
	s_waitcnt lgkmcnt(0)
	s_barrier
	ds_read_b128 v[184:187], v157 offset:38912
	ds_read_b128 v[214:217], v158
	ds_read_b128 v[188:191], v157 offset:38944
	ds_read_b128 v[218:221], v158 offset:32
	ds_read_b128 v[192:195], v157 offset:38976
	ds_read_b128 v[222:225], v158 offset:64
	ds_read_b128 v[200:203], v157 offset:39008
	ds_read_b128 v[226:229], v158 offset:96
	s_waitcnt lgkmcnt(6)
	v_mfma_f32_32x32x16_bf16 v[34:49], v[184:187], v[214:217], 0
	ds_read_b128 v[184:187], v157 offset:39040
	ds_read_b128 v[214:217], v158 offset:128
	s_waitcnt lgkmcnt(6)
	v_mfma_f32_32x32x16_bf16 v[34:49], v[188:191], v[218:221], v[34:49]
	ds_read_b128 v[188:191], v157 offset:39072
	ds_read_b128 v[218:221], v158 offset:160
	s_waitcnt lgkmcnt(6)
	v_mfma_f32_32x32x16_bf16 v[34:49], v[192:195], v[222:225], v[34:49]
	ds_read_b128 v[192:195], v157 offset:39104
	ds_read_b128 v[222:225], v158 offset:192
	s_waitcnt lgkmcnt(6)
	v_mfma_f32_32x32x16_bf16 v[34:49], v[200:203], v[226:229], v[34:49]
	ds_read_b128 v[200:203], v157 offset:39136
	ds_read_b128 v[226:229], v158 offset:224
	s_cbranch_vccz .Lgla_awave
	s_waitcnt lgkmcnt(6)
	v_mfma_f32_32x32x16_bf16 v[34:49], v[184:187], v[214:217], v[34:49]
	s_waitcnt lgkmcnt(4)
	v_mfma_f32_32x32x16_bf16 v[34:49], v[188:191], v[218:221], v[34:49]
	s_waitcnt lgkmcnt(2)
	v_mfma_f32_32x32x16_bf16 v[34:49], v[192:195], v[222:225], v[34:49]
	s_waitcnt lgkmcnt(0)
	v_mfma_f32_32x32x16_bf16 v[34:49], v[200:203], v[226:229], v[34:49]
	s_andn2_b64 vcc, exec, s[58:59]
	s_cbranch_vccnz .LBB0_662
	s_mov_b32 s2, s94
	s_mov_b32 s3, s94
	v_mov_b64_e32 v[50:51], s[2:3]
	ds_write_b64 v159, v[50:51]
	ds_write_b64 v160, v[50:51]
	ds_write_b64 v162, v[50:51]
	ds_write_b64 v163, v[50:51]
	s_branch .LBB0_662

; #define LAS __attribute__((address_space(3)))
; __device__ __forceinline__ void phase_gla(const Frame& F, int l, int gi, int ng, bool last, unsigned* cw) {
;     ...
;             if (s + 1 < 68) GLA_LOAD(s + 1);
;             { const f16x8 ga = *(const LAS f16x8*)(lds + GL_LR + ((w >> 2) * 32 + r32) * 32 + hh * 16);
;               f32x16 la;
; #pragma unroll
;               for (int e = 0; e < 16; ++e) la[e] = 0.f;
;               la = __builtin_amdgcn_mfma_f32_32x32x16_f16(ga, gwf, la, 0, 0, 0);
; #pragma unroll
;               for (int e = 0; e < 16; ++e) { const int i = (w >> 2) * 32 + (e & 3) + 8 * (e >> 2) + 4 * hh; const float lg = la[e] + gbv;
.Lgla_s1_skip:
	s_nop 11
	s_branch .LBB0_654
